# conversion tile loads use sc1 nt policy
# speedup vs baseline: 1.0046x; 1.0046x over previous
; __device__ __forceinline__ void tr_load(const TrJob& jb, int tile, int tid, f32x4 (&v)[8][2], int& k0, int& n0) {
;     const int nblk = (jb.N + 127) / 128, kt = tile / nblk, nt = tile - kt * nblk; k0 = 256 * kt; n0 = 128 * nt;
;     const int c4 = (tid & 15) + 16 * ((tid >> 6) & 1), rp = ((tid >> 4) & 3) + 4 * (tid >> 7);
;     int col = n0 + 4 * c4; col = col < jb.N - 4 ? col : jb.N - 4;
;     const float* wp = jb.W + (size_t)(k0 + 2 * rp) * jb.N + col;
; #pragma unroll
;     for (int i = 0; i < 8; ++i) { v[i][0] = *(const f32x4*)(wp + (size_t)(32 * i) * jb.N); v[i][1] = *(const f32x4*)(wp + (size_t)(32 * i + 1) * jb.N); }
;     if (jb.gain) {
; #pragma unroll
;         for (int i = 0; i < 8; ++i) { const float ga = jb.gain[k0 + 32 * i + 2 * rp], gb = jb.gain[k0 + 32 * i + 2 * rp + 1]; v[i][0] = v[i][0] * ga; v[i][1] = v[i][1] * gb; } }
; }
.LBB0_82:
	s_add_i32 s7, s6, 0x7f
	s_lshr_b32 s8, s7, 7
	v_cvt_f32_u32_e32 v2, s8
	s_sub_i32 s11, 0, s8
	s_abs_i32 s10, s17
	s_ashr_i32 s9, s17, 31
	v_rcp_iflag_f32_e32 v2, v2
	v_lshrrev_b32_e32 v3, 4, v68
	v_ashrrev_i32_e32 v72, 5, v68
	v_bfi_b32 v3, 3, v3, v72
	v_mul_f32_e32 v2, 0x4f7ffffe, v2
	v_cvt_u32_f32_e32 v2, v2
	v_and_b32_e32 v70, 64, v68
	v_lshlrev_b32_e32 v78, 1, v3
	s_mov_b32 s7, 0
	v_readfirstlane_b32 s14, v2
	s_mul_i32 s11, s11, s14
	s_mul_hi_u32 s11, s14, s11
	s_add_i32 s14, s14, s11
	s_mul_hi_u32 s11, s10, s14
	s_mul_i32 s14, s11, s8
	s_sub_i32 s10, s10, s14
	s_add_i32 s15, s11, 1
	s_sub_i32 s14, s10, s8
	s_cmp_ge_u32 s10, s8
	s_cselect_b32 s11, s15, s11
	s_cselect_b32 s10, s14, s10
	s_add_i32 s14, s11, 1
	s_cmp_ge_u32 s10, s8
	s_cselect_b32 s10, s14, s11
	s_xor_b32 s10, s10, s9
	s_sub_i32 s9, s10, s9
	s_mul_i32 s8, s9, s8
	s_sub_i32 s8, s17, s8
	v_lshlrev_b32_e32 v2, 2, v68
	s_lshl_b32 s16, s9, 8
	s_lshl_b32 s17, s8, 7
	v_and_or_b32 v77, v2, 60, v70
	v_or_b32_e32 v2, s17, v77
	s_add_i32 s8, s6, -4
	v_add_u32_e32 v66, s16, v78
	v_min_i32_e32 v2, s8, v2
	v_mad_u64_u32 v[4:5], s[8:9], v66, s6, 0
	v_ashrrev_i32_e32 v67, 31, v66
	v_mov_b32_e32 v6, v5
	v_mad_u64_u32 v[6:7], s[8:9], v67, s6, v[6:7]
	v_mov_b32_e32 v5, v6
	v_lshl_add_u64 v[4:5], v[4:5], 2, s[4:5]
	v_ashrrev_i32_e32 v3, 31, v2
	v_lshl_add_u64 v[2:3], v[2:3], 2, v[4:5]
	s_lshl_b64 s[4:5], s[6:7], 2
	v_lshl_add_u64 v[10:11], v[2:3], 0, s[4:5]
	s_mul_i32 s8, s6, 0x7c
	s_mov_b32 s9, s7
	global_load_dwordx4 v[2:5], v[2:3], off sc1 nt
	s_nop 0
	global_load_dwordx4 v[6:9], v[10:11], off sc1 nt
	v_lshl_add_u64 v[10:11], v[10:11], 0, s[8:9]
	v_lshl_add_u64 v[18:19], v[10:11], 0, s[4:5]
	global_load_dwordx4 v[10:13], v[10:11], off sc1 nt
	s_nop 0
	global_load_dwordx4 v[14:17], v[18:19], off sc1 nt
	v_lshl_add_u64 v[18:19], v[18:19], 0, s[8:9]
	v_lshl_add_u64 v[26:27], v[18:19], 0, s[4:5]
	global_load_dwordx4 v[18:21], v[18:19], off sc1 nt
	s_nop 0
	global_load_dwordx4 v[22:25], v[26:27], off sc1 nt
	v_lshl_add_u64 v[26:27], v[26:27], 0, s[8:9]
	v_lshl_add_u64 v[34:35], v[26:27], 0, s[4:5]
	v_lshl_add_u64 v[38:39], v[34:35], 0, s[8:9]
	v_lshl_add_u64 v[42:43], v[38:39], 0, s[4:5]
	v_lshl_add_u64 v[46:47], v[42:43], 0, s[8:9]
	v_lshl_add_u64 v[50:51], v[46:47], 0, s[4:5]
	global_load_dwordx4 v[26:29], v[26:27], off sc1 nt
	s_nop 0
	global_load_dwordx4 v[30:33], v[34:35], off sc1 nt
	v_bfe_u32 v71, v68, 4, 2
	global_load_dwordx4 v[34:37], v[38:39], off sc1 nt
	s_cmp_eq_u64 s[12:13], 0
	global_load_dwordx4 v[38:41], v[42:43], off sc1 nt
	v_and_b32_e32 v72, -4, v72
	global_load_dwordx4 v[42:45], v[46:47], off sc1 nt
	v_readlane_b32 s95, v252, 41
	global_load_dwordx4 v[46:49], v[50:51], off sc1 nt
	v_lshl_add_u64 v[50:51], v[50:51], 0, s[8:9]
	v_lshl_add_u64 v[54:55], v[50:51], 0, s[4:5]
	v_lshl_add_u64 v[58:59], v[54:55], 0, s[8:9]
	v_lshl_add_u64 v[62:63], v[58:59], 0, s[4:5]
	global_load_dwordx4 v[50:53], v[50:51], off sc1 nt
	s_nop 0
	global_load_dwordx4 v[54:57], v[54:55], off sc1 nt
	s_nop 0
	global_load_dwordx4 v[58:61], v[58:59], off sc1 nt
	s_nop 0
	global_load_dwordx4 v[62:65], v[62:63], off sc1 nt
	s_cbranch_scc1 .LBB0_84
	v_lshl_add_u64 v[66:67], v[66:67], 2, s[12:13]
	global_load_dwordx2 v[74:75], v[66:67], off
	global_load_dwordx2 v[80:81], v[66:67], off offset:128
	global_load_dwordx2 v[82:83], v[66:67], off offset:256
	global_load_dwordx2 v[84:85], v[66:67], off offset:384
	global_load_dwordx2 v[86:87], v[66:67], off offset:512
	global_load_dwordx2 v[88:89], v[66:67], off offset:640
	global_load_dwordx2 v[90:91], v[66:67], off offset:768
	s_nop 0
	global_load_dwordx2 v[66:67], v[66:67], off offset:896
	s_waitcnt vmcnt(7)
	v_pk_mul_f32 v[4:5], v[4:5], v[74:75] op_sel_hi:[1,0]
	v_pk_mul_f32 v[2:3], v[2:3], v[74:75] op_sel_hi:[1,0]
	v_pk_mul_f32 v[8:9], v[8:9], v[74:75] op_sel:[0,1]
	v_pk_mul_f32 v[6:7], v[6:7], v[74:75] op_sel:[0,1]
	s_waitcnt vmcnt(6)
	v_pk_mul_f32 v[12:13], v[12:13], v[80:81] op_sel_hi:[1,0]
	v_pk_mul_f32 v[10:11], v[10:11], v[80:81] op_sel_hi:[1,0]
	v_pk_mul_f32 v[16:17], v[16:17], v[80:81] op_sel:[0,1]
	v_pk_mul_f32 v[14:15], v[14:15], v[80:81] op_sel:[0,1]
	s_waitcnt vmcnt(5)
	v_pk_mul_f32 v[20:21], v[20:21], v[82:83] op_sel_hi:[1,0]
	v_pk_mul_f32 v[18:19], v[18:19], v[82:83] op_sel_hi:[1,0]
	v_pk_mul_f32 v[24:25], v[24:25], v[82:83] op_sel:[0,1]
	v_pk_mul_f32 v[22:23], v[22:23], v[82:83] op_sel:[0,1]
	s_waitcnt vmcnt(4)
	v_pk_mul_f32 v[28:29], v[28:29], v[84:85] op_sel_hi:[1,0]
	v_pk_mul_f32 v[26:27], v[26:27], v[84:85] op_sel_hi:[1,0]
	v_pk_mul_f32 v[32:33], v[32:33], v[84:85] op_sel:[0,1]
	v_pk_mul_f32 v[30:31], v[30:31], v[84:85] op_sel:[0,1]
	s_waitcnt vmcnt(3)
	v_pk_mul_f32 v[36:37], v[36:37], v[86:87] op_sel_hi:[1,0]
	v_pk_mul_f32 v[34:35], v[34:35], v[86:87] op_sel_hi:[1,0]
	v_pk_mul_f32 v[40:41], v[40:41], v[86:87] op_sel:[0,1]
	v_pk_mul_f32 v[38:39], v[38:39], v[86:87] op_sel:[0,1]
	s_waitcnt vmcnt(2)
	v_pk_mul_f32 v[44:45], v[44:45], v[88:89] op_sel_hi:[1,0]
	v_pk_mul_f32 v[42:43], v[42:43], v[88:89] op_sel_hi:[1,0]
	v_pk_mul_f32 v[48:49], v[48:49], v[88:89] op_sel:[0,1]
	v_pk_mul_f32 v[46:47], v[46:47], v[88:89] op_sel:[0,1]
	s_waitcnt vmcnt(1)
	v_pk_mul_f32 v[52:53], v[52:53], v[90:91] op_sel_hi:[1,0]
	v_pk_mul_f32 v[50:51], v[50:51], v[90:91] op_sel_hi:[1,0]
	v_pk_mul_f32 v[56:57], v[56:57], v[90:91] op_sel:[0,1]
	v_pk_mul_f32 v[54:55], v[54:55], v[90:91] op_sel:[0,1]
	s_waitcnt vmcnt(0)
	v_pk_mul_f32 v[60:61], v[60:61], v[66:67] op_sel_hi:[1,0]
	v_pk_mul_f32 v[58:59], v[58:59], v[66:67] op_sel_hi:[1,0]
	v_pk_mul_f32 v[64:65], v[64:65], v[66:67] op_sel:[0,1]
	v_pk_mul_f32 v[62:63], v[62:63], v[66:67] op_sel:[0,1]

; __device__ __forceinline__ void tr_load(const TrJob& jb, int tile, int tid, f32x4 (&v)[8][2], int& k0, int& n0) {
;     const int nblk = (jb.N + 127) / 128, kt = tile / nblk, nt = tile - kt * nblk; k0 = 256 * kt; n0 = 128 * nt;
;     const int c4 = (tid & 15) + 16 * ((tid >> 6) & 1), rp = ((tid >> 4) & 3) + 4 * (tid >> 7);
;     int col = n0 + 4 * c4; col = col < jb.N - 4 ? col : jb.N - 4;
;     const float* wp = jb.W + (size_t)(k0 + 2 * rp) * jb.N + col;
; #pragma unroll
;     for (int i = 0; i < 8; ++i) { v[i][0] = *(const f32x4*)(wp + (size_t)(32 * i) * jb.N); v[i][1] = *(const f32x4*)(wp + (size_t)(32 * i + 1) * jb.N); }
;     if (jb.gain) {
; #pragma unroll
;         for (int i = 0; i < 8; ++i) { const float ga = jb.gain[k0 + 32 * i + 2 * rp], gb = jb.gain[k0 + 32 * i + 2 * rp + 1]; v[i][0] = v[i][0] * ga; v[i][1] = v[i][1] * gb; } }
; }
.LBB0_125:
	s_add_i32 s12, s6, 0x7f
	s_lshr_b32 s12, s12, 7
	v_cvt_f32_u32_e32 v2, s12
	s_sub_i32 s17, 0, s12
	s_abs_i32 s16, s45
	s_ashr_i32 s13, s45, 31
	v_rcp_iflag_f32_e32 v2, v2
	s_nop 0
	v_mul_f32_e32 v2, 0x4f7ffffe, v2
	v_cvt_u32_f32_e32 v2, v2
	s_nop 0
	v_readfirstlane_b32 s18, v2
	s_mul_i32 s17, s17, s18
	s_mul_hi_u32 s17, s18, s17
	s_add_i32 s18, s18, s17
	s_mul_hi_u32 s17, s16, s18
	s_mul_i32 s18, s17, s12
	s_sub_i32 s16, s16, s18
	s_add_i32 s19, s17, 1
	s_sub_i32 s18, s16, s12
	s_cmp_ge_u32 s16, s12
	s_cselect_b32 s17, s19, s17
	s_cselect_b32 s16, s18, s16
	s_add_i32 s18, s17, 1
	s_cmp_ge_u32 s16, s12
	s_cselect_b32 s16, s18, s17
	s_xor_b32 s16, s16, s13
	s_sub_i32 s13, s16, s13
	s_mul_i32 s12, s13, s12
	s_lshl_b32 s16, s13, 8
	s_sub_i32 s12, s45, s12
	v_add_u32_e32 v66, s16, v78
	s_lshl_b32 s17, s12, 7
	v_mad_u64_u32 v[4:5], s[12:13], v66, s6, 0
	v_ashrrev_i32_e32 v67, 31, v66
	v_mov_b32_e32 v6, v5
	s_add_i32 s18, s6, -4
	v_or_b32_e32 v2, s17, v77
	v_mad_u64_u32 v[6:7], s[12:13], v67, s6, v[6:7]
	v_min_i32_e32 v2, s18, v2
	v_mov_b32_e32 v5, v6
	v_lshl_add_u64 v[4:5], v[4:5], 2, s[14:15]
	v_ashrrev_i32_e32 v3, 31, v2
	v_lshl_add_u64 v[2:3], v[2:3], 2, v[4:5]
	s_lshl_b64 s[12:13], s[6:7], 2
	v_lshl_add_u64 v[10:11], v[2:3], 0, s[12:13]
	s_mul_i32 s14, s6, 0x7c
	s_mov_b32 s15, s7
	global_load_dwordx4 v[2:5], v[2:3], off sc1 nt
	s_nop 0
	global_load_dwordx4 v[6:9], v[10:11], off sc1 nt
	v_lshl_add_u64 v[10:11], v[10:11], 0, s[14:15]
	v_lshl_add_u64 v[18:19], v[10:11], 0, s[12:13]
	global_load_dwordx4 v[10:13], v[10:11], off sc1 nt
	s_nop 0
	global_load_dwordx4 v[14:17], v[18:19], off sc1 nt
	v_lshl_add_u64 v[18:19], v[18:19], 0, s[14:15]
	v_lshl_add_u64 v[26:27], v[18:19], 0, s[12:13]
	global_load_dwordx4 v[18:21], v[18:19], off sc1 nt
	s_nop 0
	global_load_dwordx4 v[22:25], v[26:27], off sc1 nt
	v_lshl_add_u64 v[26:27], v[26:27], 0, s[14:15]
	v_lshl_add_u64 v[34:35], v[26:27], 0, s[12:13]
	v_lshl_add_u64 v[38:39], v[34:35], 0, s[14:15]
	v_lshl_add_u64 v[42:43], v[38:39], 0, s[12:13]
	v_lshl_add_u64 v[46:47], v[42:43], 0, s[14:15]
	v_lshl_add_u64 v[50:51], v[46:47], 0, s[12:13]
	v_lshl_add_u64 v[54:55], v[50:51], 0, s[14:15]
	v_lshl_add_u64 v[58:59], v[54:55], 0, s[12:13]
	v_lshl_add_u64 v[62:63], v[58:59], 0, s[14:15]
	global_load_dwordx4 v[26:29], v[26:27], off sc1 nt
	s_nop 0
	global_load_dwordx4 v[30:33], v[34:35], off sc1 nt
	s_cmp_eq_u64 s[10:11], 0
	global_load_dwordx4 v[34:37], v[38:39], off sc1 nt
	s_nop 0
	global_load_dwordx4 v[38:41], v[42:43], off sc1 nt
	s_nop 0
	global_load_dwordx4 v[42:45], v[46:47], off sc1 nt
	s_nop 0
	global_load_dwordx4 v[46:49], v[50:51], off sc1 nt
	s_nop 0
	global_load_dwordx4 v[50:53], v[54:55], off sc1 nt
	s_nop 0
	global_load_dwordx4 v[54:57], v[58:59], off sc1 nt
	s_nop 0
	global_load_dwordx4 v[58:61], v[62:63], off sc1 nt
	v_lshl_add_u64 v[62:63], v[62:63], 0, s[12:13]
	global_load_dwordx4 v[62:65], v[62:63], off sc1 nt
	s_cbranch_scc1 .LBB0_127
	v_lshl_add_u64 v[68:69], v[66:67], 2, s[10:11]
	v_add_u32_e32 v72, 32, v66
	v_add_u32_e32 v74, 64, v66
	v_add_u32_e32 v94, 0x60, v66
	v_add_u32_e32 v96, 0x80, v66
	v_add_u32_e32 v98, 0xa0, v66
	v_add_u32_e32 v100, 0xc0, v66
	v_add_u32_e32 v66, 0xe0, v66
	v_ashrrev_i32_e32 v73, 31, v72
	v_ashrrev_i32_e32 v75, 31, v74
	v_ashrrev_i32_e32 v95, 31, v94
	v_ashrrev_i32_e32 v97, 31, v96
	v_ashrrev_i32_e32 v99, 31, v98
	v_ashrrev_i32_e32 v101, 31, v100
	v_ashrrev_i32_e32 v67, 31, v66
	v_lshl_add_u64 v[72:73], v[72:73], 2, s[10:11]
	v_lshl_add_u64 v[74:75], v[74:75], 2, s[10:11]
	v_lshl_add_u64 v[94:95], v[94:95], 2, s[10:11]
	v_lshl_add_u64 v[96:97], v[96:97], 2, s[10:11]
	v_lshl_add_u64 v[98:99], v[98:99], 2, s[10:11]
	v_lshl_add_u64 v[100:101], v[100:101], 2, s[10:11]
	v_lshl_add_u64 v[66:67], v[66:67], 2, s[10:11]
	global_load_dwordx2 v[68:69], v[68:69], off
	s_nop 0
	global_load_dwordx2 v[72:73], v[72:73], off
	s_nop 0
	global_load_dwordx2 v[74:75], v[74:75], off
	s_waitcnt vmcnt(1)
	v_pk_mul_f32 v[12:13], v[12:13], v[72:73] op_sel_hi:[1,0]
	global_load_dwordx2 v[94:95], v[94:95], off
	v_pk_mul_f32 v[10:11], v[10:11], v[72:73] op_sel_hi:[1,0]
	global_load_dwordx2 v[96:97], v[96:97], off
	v_pk_mul_f32 v[16:17], v[16:17], v[72:73] op_sel:[0,1]
	global_load_dwordx2 v[98:99], v[98:99], off
	v_pk_mul_f32 v[14:15], v[14:15], v[72:73] op_sel:[0,1]
	global_load_dwordx2 v[100:101], v[100:101], off
	s_waitcnt vmcnt(4)
	v_pk_mul_f32 v[20:21], v[20:21], v[74:75] op_sel_hi:[1,0]
	global_load_dwordx2 v[66:67], v[66:67], off
	v_pk_mul_f32 v[4:5], v[4:5], v[68:69] op_sel_hi:[1,0]
	v_pk_mul_f32 v[2:3], v[2:3], v[68:69] op_sel_hi:[1,0]
	v_pk_mul_f32 v[8:9], v[8:9], v[68:69] op_sel:[0,1]
	v_pk_mul_f32 v[6:7], v[6:7], v[68:69] op_sel:[0,1]
	v_pk_mul_f32 v[18:19], v[18:19], v[74:75] op_sel_hi:[1,0]
	v_pk_mul_f32 v[24:25], v[24:25], v[74:75] op_sel:[0,1]
	v_pk_mul_f32 v[22:23], v[22:23], v[74:75] op_sel:[0,1]
	s_waitcnt vmcnt(4)
	v_pk_mul_f32 v[28:29], v[28:29], v[94:95] op_sel_hi:[1,0]
	v_pk_mul_f32 v[26:27], v[26:27], v[94:95] op_sel_hi:[1,0]
	v_pk_mul_f32 v[32:33], v[32:33], v[94:95] op_sel:[0,1]
	v_pk_mul_f32 v[30:31], v[30:31], v[94:95] op_sel:[0,1]
	s_waitcnt vmcnt(3)
	v_pk_mul_f32 v[36:37], v[36:37], v[96:97] op_sel_hi:[1,0]
	v_pk_mul_f32 v[34:35], v[34:35], v[96:97] op_sel_hi:[1,0]
	v_pk_mul_f32 v[40:41], v[40:41], v[96:97] op_sel:[0,1]
	v_pk_mul_f32 v[38:39], v[38:39], v[96:97] op_sel:[0,1]
	s_waitcnt vmcnt(2)
	v_pk_mul_f32 v[44:45], v[44:45], v[98:99] op_sel_hi:[1,0]
	v_pk_mul_f32 v[42:43], v[42:43], v[98:99] op_sel_hi:[1,0]
	v_pk_mul_f32 v[48:49], v[48:49], v[98:99] op_sel:[0,1]
	v_pk_mul_f32 v[46:47], v[46:47], v[98:99] op_sel:[0,1]
	s_waitcnt vmcnt(1)
	v_pk_mul_f32 v[52:53], v[52:53], v[100:101] op_sel_hi:[1,0]
	v_pk_mul_f32 v[50:51], v[50:51], v[100:101] op_sel_hi:[1,0]
	v_pk_mul_f32 v[56:57], v[56:57], v[100:101] op_sel:[0,1]
	v_pk_mul_f32 v[54:55], v[54:55], v[100:101] op_sel:[0,1]
	s_waitcnt vmcnt(0)
	v_pk_mul_f32 v[60:61], v[60:61], v[66:67] op_sel_hi:[1,0]
	v_pk_mul_f32 v[58:59], v[58:59], v[66:67] op_sel_hi:[1,0]
	v_pk_mul_f32 v[64:65], v[64:65], v[66:67] op_sel:[0,1]
	v_pk_mul_f32 v[62:63], v[62:63], v[66:67] op_sel:[0,1]

; __device__ __forceinline__ void tr_load(const TrJob& jb, int tile, int tid, f32x4 (&v)[8][2], int& k0, int& n0) {
;     const int nblk = (jb.N + 127) / 128, kt = tile / nblk, nt = tile - kt * nblk; k0 = 256 * kt; n0 = 128 * nt;
;     const int c4 = (tid & 15) + 16 * ((tid >> 6) & 1), rp = ((tid >> 4) & 3) + 4 * (tid >> 7);
;     int col = n0 + 4 * c4; col = col < jb.N - 4 ? col : jb.N - 4;
;     const float* wp = jb.W + (size_t)(k0 + 2 * rp) * jb.N + col;
; #pragma unroll
;     for (int i = 0; i < 8; ++i) { v[i][0] = *(const f32x4*)(wp + (size_t)(32 * i) * jb.N); v[i][1] = *(const f32x4*)(wp + (size_t)(32 * i + 1) * jb.N); }
;     if (jb.gain) {
; #pragma unroll
;         for (int i = 0; i < 8; ++i) { const float ga = jb.gain[k0 + 32 * i + 2 * rp], gb = jb.gain[k0 + 32 * i + 2 * rp + 1]; v[i][0] = v[i][0] * ga; v[i][1] = v[i][1] * gb; } }
; }
.LBB0_343:
	s_add_i32 s6, s34, 0x7f
	s_lshr_b32 s6, s6, 7
	v_cvt_f32_u32_e32 v4, s6
	s_sub_i32 s9, 0, s6
	s_abs_i32 s8, s15
	s_ashr_i32 s7, s15, 31
	v_rcp_iflag_f32_e32 v4, v4
	v_lshrrev_b32_e32 v5, 4, v2
	v_ashrrev_i32_e32 v71, 5, v2
	v_bfi_b32 v5, 3, v5, v71
	v_mul_f32_e32 v4, 0x4f7ffffe, v4
	v_cvt_u32_f32_e32 v4, v4
	v_and_b32_e32 v70, 64, v2
	v_lshlrev_b32_e32 v78, 1, v5
	v_readfirstlane_b32 s12, v4
	s_mul_i32 s9, s9, s12
	s_mul_hi_u32 s9, s12, s9
	s_add_i32 s12, s12, s9
	s_mul_hi_u32 s9, s8, s12
	s_mul_i32 s12, s9, s6
	s_sub_i32 s8, s8, s12
	s_add_i32 s13, s9, 1
	s_sub_i32 s12, s8, s6
	s_cmp_ge_u32 s8, s6
	s_cselect_b32 s9, s13, s9
	s_cselect_b32 s8, s12, s8
	s_add_i32 s12, s9, 1
	s_cmp_ge_u32 s8, s6
	s_cselect_b32 s8, s12, s9
	s_xor_b32 s8, s8, s7
	s_sub_i32 s7, s8, s7
	s_mul_i32 s6, s7, s6
	s_sub_i32 s6, s15, s6
	v_lshlrev_b32_e32 v4, 2, v2
	s_lshl_b32 s14, s7, 8
	s_lshl_b32 s15, s6, 7
	v_and_or_b32 v77, v4, 60, v70
	v_or_b32_e32 v4, s15, v77
	s_add_i32 s6, s34, -4
	v_add_u32_e32 v68, s14, v78
	v_min_i32_e32 v4, s6, v4
	s_waitcnt vmcnt(12)
	v_mad_u64_u32 v[6:7], s[6:7], v68, s34, 0
	v_ashrrev_i32_e32 v69, 31, v68
	v_mov_b32_e32 v8, v7
	v_mad_u64_u32 v[8:9], s[6:7], v69, s34, v[8:9]
	v_mov_b32_e32 v7, v8
	v_lshl_add_u64 v[6:7], v[6:7], 2, s[4:5]
	v_ashrrev_i32_e32 v5, 31, v4
	v_lshl_add_u64 v[4:5], v[4:5], 2, v[6:7]
	s_lshl_b64 s[4:5], s[34:35], 2
	s_waitcnt vmcnt(11)
	v_lshl_add_u64 v[12:13], v[4:5], 0, s[4:5]
	s_mul_i32 s6, s34, 0x7c
	s_mov_b32 s7, s35
	global_load_dwordx4 v[4:7], v[4:5], off sc1 nt
	s_nop 0
	global_load_dwordx4 v[8:11], v[12:13], off sc1 nt
	v_lshl_add_u64 v[12:13], v[12:13], 0, s[6:7]
	s_waitcnt vmcnt(11)
	v_lshl_add_u64 v[20:21], v[12:13], 0, s[4:5]
	global_load_dwordx4 v[12:15], v[12:13], off sc1 nt
	s_nop 0
	global_load_dwordx4 v[16:19], v[20:21], off sc1 nt
	v_lshl_add_u64 v[20:21], v[20:21], 0, s[6:7]
	s_waitcnt vmcnt(12)
	v_lshl_add_u64 v[28:29], v[20:21], 0, s[4:5]
	global_load_dwordx4 v[20:23], v[20:21], off sc1 nt
	s_nop 0
	global_load_dwordx4 v[24:27], v[28:29], off sc1 nt
	v_lshl_add_u64 v[28:29], v[28:29], 0, s[6:7]
	s_waitcnt vmcnt(13)
	v_lshl_add_u64 v[36:37], v[28:29], 0, s[4:5]
	s_waitcnt vmcnt(12)
	v_lshl_add_u64 v[40:41], v[36:37], 0, s[6:7]
	s_waitcnt vmcnt(11)
	v_lshl_add_u64 v[44:45], v[40:41], 0, s[4:5]
	s_waitcnt vmcnt(10)
	v_lshl_add_u64 v[48:49], v[44:45], 0, s[6:7]
	s_waitcnt vmcnt(9)
	v_lshl_add_u64 v[52:53], v[48:49], 0, s[4:5]
	s_waitcnt vmcnt(8)
	v_lshl_add_u64 v[56:57], v[52:53], 0, s[6:7]
	s_waitcnt vmcnt(7)
	v_lshl_add_u64 v[60:61], v[56:57], 0, s[4:5]
	s_waitcnt vmcnt(6)
	v_lshl_add_u64 v[64:65], v[60:61], 0, s[6:7]
	global_load_dwordx4 v[28:31], v[28:29], off sc1 nt
	s_nop 0
	global_load_dwordx4 v[32:35], v[36:37], off sc1 nt
	s_cmp_eq_u64 s[10:11], 0
	global_load_dwordx4 v[36:39], v[40:41], off sc1 nt
	s_nop 0
	global_load_dwordx4 v[40:43], v[44:45], off sc1 nt
	s_nop 0
	global_load_dwordx4 v[44:47], v[48:49], off sc1 nt
	s_nop 0
	global_load_dwordx4 v[48:51], v[52:53], off sc1 nt
	s_nop 0
	global_load_dwordx4 v[52:55], v[56:57], off sc1 nt
	s_nop 0
	global_load_dwordx4 v[56:59], v[60:61], off sc1 nt
	s_nop 0
	global_load_dwordx4 v[60:63], v[64:65], off sc1 nt
	v_lshl_add_u64 v[64:65], v[64:65], 0, s[4:5]
	global_load_dwordx4 v[64:67], v[64:65], off sc1 nt
	s_cbranch_scc1 .LBB0_345
	v_lshl_add_u64 v[68:69], v[68:69], 2, s[10:11]
	global_load_dwordx2 v[72:73], v[68:69], off
	s_waitcnt vmcnt(0)
	v_pk_mul_f32 v[6:7], v[6:7], v[72:73] op_sel_hi:[1,0]
	v_pk_mul_f32 v[4:5], v[4:5], v[72:73] op_sel_hi:[1,0]
	v_pk_mul_f32 v[10:11], v[10:11], v[72:73] op_sel:[0,1]
	v_pk_mul_f32 v[8:9], v[8:9], v[72:73] op_sel:[0,1]
	global_load_dwordx2 v[72:73], v[68:69], off offset:128
	s_waitcnt vmcnt(0)
	v_pk_mul_f32 v[14:15], v[14:15], v[72:73] op_sel_hi:[1,0]
	v_pk_mul_f32 v[12:13], v[12:13], v[72:73] op_sel_hi:[1,0]
	v_pk_mul_f32 v[18:19], v[18:19], v[72:73] op_sel:[0,1]
	v_pk_mul_f32 v[16:17], v[16:17], v[72:73] op_sel:[0,1]
	global_load_dwordx2 v[72:73], v[68:69], off offset:256
	s_waitcnt vmcnt(0)
	v_pk_mul_f32 v[22:23], v[22:23], v[72:73] op_sel_hi:[1,0]
	v_pk_mul_f32 v[20:21], v[20:21], v[72:73] op_sel_hi:[1,0]
	v_pk_mul_f32 v[26:27], v[26:27], v[72:73] op_sel:[0,1]
	v_pk_mul_f32 v[24:25], v[24:25], v[72:73] op_sel:[0,1]
	global_load_dwordx2 v[72:73], v[68:69], off offset:384
	s_waitcnt vmcnt(0)
	v_pk_mul_f32 v[30:31], v[30:31], v[72:73] op_sel_hi:[1,0]
	v_pk_mul_f32 v[28:29], v[28:29], v[72:73] op_sel_hi:[1,0]
	v_pk_mul_f32 v[34:35], v[34:35], v[72:73] op_sel:[0,1]
	v_pk_mul_f32 v[32:33], v[32:33], v[72:73] op_sel:[0,1]
	global_load_dwordx2 v[72:73], v[68:69], off offset:512
	s_waitcnt vmcnt(0)
	v_pk_mul_f32 v[38:39], v[38:39], v[72:73] op_sel_hi:[1,0]
	v_pk_mul_f32 v[36:37], v[36:37], v[72:73] op_sel_hi:[1,0]
	v_pk_mul_f32 v[42:43], v[42:43], v[72:73] op_sel:[0,1]
	v_pk_mul_f32 v[40:41], v[40:41], v[72:73] op_sel:[0,1]
	global_load_dwordx2 v[72:73], v[68:69], off offset:640
	s_waitcnt vmcnt(0)
	v_pk_mul_f32 v[46:47], v[46:47], v[72:73] op_sel_hi:[1,0]
	v_pk_mul_f32 v[44:45], v[44:45], v[72:73] op_sel_hi:[1,0]
	v_pk_mul_f32 v[50:51], v[50:51], v[72:73] op_sel:[0,1]
	v_pk_mul_f32 v[48:49], v[48:49], v[72:73] op_sel:[0,1]
	global_load_dwordx2 v[72:73], v[68:69], off offset:768
	s_waitcnt vmcnt(0)
	v_pk_mul_f32 v[54:55], v[54:55], v[72:73] op_sel_hi:[1,0]
	global_load_dwordx2 v[68:69], v[68:69], off offset:896
	v_pk_mul_f32 v[52:53], v[52:53], v[72:73] op_sel_hi:[1,0]
	v_pk_mul_f32 v[58:59], v[58:59], v[72:73] op_sel:[0,1]
	v_pk_mul_f32 v[56:57], v[56:57], v[72:73] op_sel:[0,1]
	s_waitcnt vmcnt(0)
	v_pk_mul_f32 v[62:63], v[62:63], v[68:69] op_sel_hi:[1,0]
	v_pk_mul_f32 v[60:61], v[60:61], v[68:69] op_sel_hi:[1,0]
	v_pk_mul_f32 v[66:67], v[66:67], v[68:69] op_sel:[0,1]
	v_pk_mul_f32 v[64:65], v[64:65], v[68:69] op_sel:[0,1]

; __device__ __forceinline__ void tr_load(const TrJob& jb, int tile, int tid, f32x4 (&v)[8][2], int& k0, int& n0) {
;     const int nblk = (jb.N + 127) / 128, kt = tile / nblk, nt = tile - kt * nblk; k0 = 256 * kt; n0 = 128 * nt;
;     const int c4 = (tid & 15) + 16 * ((tid >> 6) & 1), rp = ((tid >> 4) & 3) + 4 * (tid >> 7);
;     int col = n0 + 4 * c4; col = col < jb.N - 4 ? col : jb.N - 4;
;     const float* wp = jb.W + (size_t)(k0 + 2 * rp) * jb.N + col;
; #pragma unroll
;     for (int i = 0; i < 8; ++i) { v[i][0] = *(const f32x4*)(wp + (size_t)(32 * i) * jb.N); v[i][1] = *(const f32x4*)(wp + (size_t)(32 * i + 1) * jb.N); }
;     if (jb.gain) {
; #pragma unroll
;         for (int i = 0; i < 8; ++i) { const float ga = jb.gain[k0 + 32 * i + 2 * rp], gb = jb.gain[k0 + 32 * i + 2 * rp + 1]; v[i][0] = v[i][0] * ga; v[i][1] = v[i][1] * gb; } }
; }
.LBB0_385:
	s_add_i32 s10, s34, 0x7f
	s_lshr_b32 s10, s10, 7
	v_cvt_f32_u32_e32 v2, s10
	s_sub_i32 s15, 0, s10
	s_abs_i32 s14, s40
	s_ashr_i32 s11, s40, 31
	v_rcp_iflag_f32_e32 v2, v2
	s_nop 0
	v_mul_f32_e32 v2, 0x4f7ffffe, v2
	v_cvt_u32_f32_e32 v2, v2
	s_nop 0
	v_readfirstlane_b32 s16, v2
	s_mul_i32 s15, s15, s16
	s_mul_hi_u32 s15, s16, s15
	s_add_i32 s16, s16, s15
	s_mul_hi_u32 s15, s14, s16
	s_mul_i32 s16, s15, s10
	s_sub_i32 s14, s14, s16
	s_add_i32 s17, s15, 1
	s_sub_i32 s16, s14, s10
	s_cmp_ge_u32 s14, s10
	s_cselect_b32 s15, s17, s15
	s_cselect_b32 s14, s16, s14
	s_add_i32 s16, s15, 1
	s_cmp_ge_u32 s14, s10
	s_cselect_b32 s14, s16, s15
	s_xor_b32 s14, s14, s11
	s_sub_i32 s11, s14, s11
	s_mul_i32 s10, s11, s10
	s_lshl_b32 s14, s11, 8
	s_sub_i32 s10, s40, s10
	v_add_u32_e32 v68, s14, v78
	s_lshl_b32 s15, s10, 7
	s_add_i32 s16, s34, -4
	v_or_b32_e32 v2, s15, v77
	v_mad_u64_u32 v[6:7], s[10:11], v68, s34, 0
	v_ashrrev_i32_e32 v69, 31, v68
	v_min_i32_e32 v4, s16, v2
	v_mov_b32_e32 v2, v7
	v_mad_u64_u32 v[8:9], s[10:11], v69, s34, v[2:3]
	v_mov_b32_e32 v7, v8
	v_lshl_add_u64 v[6:7], v[6:7], 2, s[12:13]
	v_ashrrev_i32_e32 v5, 31, v4
	v_lshl_add_u64 v[4:5], v[4:5], 2, v[6:7]
	s_lshl_b64 s[10:11], s[34:35], 2
	v_lshl_add_u64 v[12:13], v[4:5], 0, s[10:11]
	s_mul_i32 s12, s34, 0x7c
	s_mov_b32 s13, s35
	global_load_dwordx4 v[4:7], v[4:5], off sc1 nt
	s_nop 0
	global_load_dwordx4 v[8:11], v[12:13], off sc1 nt
	v_lshl_add_u64 v[12:13], v[12:13], 0, s[12:13]
	v_lshl_add_u64 v[20:21], v[12:13], 0, s[10:11]
	global_load_dwordx4 v[12:15], v[12:13], off sc1 nt
	s_nop 0
	global_load_dwordx4 v[16:19], v[20:21], off sc1 nt
	v_lshl_add_u64 v[20:21], v[20:21], 0, s[12:13]
	v_lshl_add_u64 v[28:29], v[20:21], 0, s[10:11]
	global_load_dwordx4 v[20:23], v[20:21], off sc1 nt
	s_nop 0
	global_load_dwordx4 v[24:27], v[28:29], off sc1 nt
	v_lshl_add_u64 v[28:29], v[28:29], 0, s[12:13]
	v_lshl_add_u64 v[36:37], v[28:29], 0, s[10:11]
	v_lshl_add_u64 v[40:41], v[36:37], 0, s[12:13]
	v_lshl_add_u64 v[44:45], v[40:41], 0, s[10:11]
	v_lshl_add_u64 v[48:49], v[44:45], 0, s[12:13]
	v_lshl_add_u64 v[52:53], v[48:49], 0, s[10:11]
	v_lshl_add_u64 v[56:57], v[52:53], 0, s[12:13]
	v_lshl_add_u64 v[60:61], v[56:57], 0, s[10:11]
	v_lshl_add_u64 v[64:65], v[60:61], 0, s[12:13]
	global_load_dwordx4 v[28:31], v[28:29], off sc1 nt
	s_nop 0
	global_load_dwordx4 v[32:35], v[36:37], off sc1 nt
	s_cmp_eq_u64 s[8:9], 0
	global_load_dwordx4 v[36:39], v[40:41], off sc1 nt
	s_nop 0
	global_load_dwordx4 v[40:43], v[44:45], off sc1 nt
	s_nop 0
	global_load_dwordx4 v[44:47], v[48:49], off sc1 nt
	s_nop 0
	global_load_dwordx4 v[48:51], v[52:53], off sc1 nt
	s_nop 0
	global_load_dwordx4 v[52:55], v[56:57], off sc1 nt
	s_nop 0
	global_load_dwordx4 v[56:59], v[60:61], off sc1 nt
	s_nop 0
	global_load_dwordx4 v[60:63], v[64:65], off sc1 nt
	v_lshl_add_u64 v[64:65], v[64:65], 0, s[10:11]
	global_load_dwordx4 v[64:67], v[64:65], off sc1 nt
	s_cbranch_scc1 .LBB0_387
	v_lshl_add_u64 v[70:71], v[68:69], 2, s[8:9]
	global_load_dwordx2 v[70:71], v[70:71], off
	s_waitcnt vmcnt(0)
	v_pk_mul_f32 v[6:7], v[6:7], v[70:71] op_sel_hi:[1,0]
	v_pk_mul_f32 v[4:5], v[4:5], v[70:71] op_sel_hi:[1,0]
	v_pk_mul_f32 v[10:11], v[10:11], v[70:71] op_sel:[0,1]
	v_pk_mul_f32 v[8:9], v[8:9], v[70:71] op_sel:[0,1]
	v_add_u32_e32 v70, 32, v68
	v_ashrrev_i32_e32 v71, 31, v70
	v_lshl_add_u64 v[70:71], v[70:71], 2, s[8:9]
	global_load_dwordx2 v[70:71], v[70:71], off
	s_waitcnt vmcnt(0)
	v_pk_mul_f32 v[14:15], v[14:15], v[70:71] op_sel_hi:[1,0]
	v_pk_mul_f32 v[12:13], v[12:13], v[70:71] op_sel_hi:[1,0]
	v_pk_mul_f32 v[18:19], v[18:19], v[70:71] op_sel:[0,1]
	v_pk_mul_f32 v[16:17], v[16:17], v[70:71] op_sel:[0,1]
	v_add_u32_e32 v70, 64, v68
	v_ashrrev_i32_e32 v71, 31, v70
	v_lshl_add_u64 v[70:71], v[70:71], 2, s[8:9]
	global_load_dwordx2 v[70:71], v[70:71], off
	s_waitcnt vmcnt(0)
	v_pk_mul_f32 v[22:23], v[22:23], v[70:71] op_sel_hi:[1,0]
	v_pk_mul_f32 v[20:21], v[20:21], v[70:71] op_sel_hi:[1,0]
	v_pk_mul_f32 v[26:27], v[26:27], v[70:71] op_sel:[0,1]
	v_pk_mul_f32 v[24:25], v[24:25], v[70:71] op_sel:[0,1]
	v_add_u32_e32 v70, 0x60, v68
	v_ashrrev_i32_e32 v71, 31, v70
	v_lshl_add_u64 v[70:71], v[70:71], 2, s[8:9]
	global_load_dwordx2 v[70:71], v[70:71], off
	s_waitcnt vmcnt(0)
	v_pk_mul_f32 v[30:31], v[30:31], v[70:71] op_sel_hi:[1,0]
	v_pk_mul_f32 v[28:29], v[28:29], v[70:71] op_sel_hi:[1,0]
	v_pk_mul_f32 v[34:35], v[34:35], v[70:71] op_sel:[0,1]
	v_pk_mul_f32 v[32:33], v[32:33], v[70:71] op_sel:[0,1]
	v_add_u32_e32 v70, 0x80, v68
	v_ashrrev_i32_e32 v71, 31, v70
	v_lshl_add_u64 v[70:71], v[70:71], 2, s[8:9]
	global_load_dwordx2 v[70:71], v[70:71], off
	s_waitcnt vmcnt(0)
	v_pk_mul_f32 v[38:39], v[38:39], v[70:71] op_sel_hi:[1,0]
	v_pk_mul_f32 v[36:37], v[36:37], v[70:71] op_sel_hi:[1,0]
	v_pk_mul_f32 v[42:43], v[42:43], v[70:71] op_sel:[0,1]
	v_pk_mul_f32 v[40:41], v[40:41], v[70:71] op_sel:[0,1]
	v_add_u32_e32 v70, 0xa0, v68
	v_ashrrev_i32_e32 v71, 31, v70
	v_lshl_add_u64 v[70:71], v[70:71], 2, s[8:9]
	global_load_dwordx2 v[70:71], v[70:71], off
	s_waitcnt vmcnt(0)
	v_pk_mul_f32 v[46:47], v[46:47], v[70:71] op_sel_hi:[1,0]
	v_pk_mul_f32 v[44:45], v[44:45], v[70:71] op_sel_hi:[1,0]
	v_pk_mul_f32 v[50:51], v[50:51], v[70:71] op_sel:[0,1]
	v_pk_mul_f32 v[48:49], v[48:49], v[70:71] op_sel:[0,1]
	v_add_u32_e32 v70, 0xc0, v68
	v_add_u32_e32 v68, 0xe0, v68
	v_ashrrev_i32_e32 v71, 31, v70
	v_ashrrev_i32_e32 v69, 31, v68
	v_lshl_add_u64 v[70:71], v[70:71], 2, s[8:9]
	v_lshl_add_u64 v[68:69], v[68:69], 2, s[8:9]
	global_load_dwordx2 v[70:71], v[70:71], off
	s_nop 0
	global_load_dwordx2 v[68:69], v[68:69], off
	s_waitcnt vmcnt(1)
	v_pk_mul_f32 v[54:55], v[54:55], v[70:71] op_sel_hi:[1,0]
	v_pk_mul_f32 v[52:53], v[52:53], v[70:71] op_sel_hi:[1,0]
	v_pk_mul_f32 v[58:59], v[58:59], v[70:71] op_sel:[0,1]
	v_pk_mul_f32 v[56:57], v[56:57], v[70:71] op_sel:[0,1]
	s_waitcnt vmcnt(0)
	v_pk_mul_f32 v[62:63], v[62:63], v[68:69] op_sel_hi:[1,0]
	v_pk_mul_f32 v[60:61], v[60:61], v[68:69] op_sel_hi:[1,0]
	v_pk_mul_f32 v[66:67], v[66:67], v[68:69] op_sel:[0,1]
	v_pk_mul_f32 v[64:65], v[64:65], v[68:69] op_sel:[0,1]

; __device__ __forceinline__ void tr_load(const TrJob& jb, int tile, int tid, f32x4 (&v)[8][2], int& k0, int& n0) {
;     const int nblk = (jb.N + 127) / 128, kt = tile / nblk, nt = tile - kt * nblk; k0 = 256 * kt; n0 = 128 * nt;
;     const int c4 = (tid & 15) + 16 * ((tid >> 6) & 1), rp = ((tid >> 4) & 3) + 4 * (tid >> 7);
;     int col = n0 + 4 * c4; col = col < jb.N - 4 ? col : jb.N - 4;
;     const float* wp = jb.W + (size_t)(k0 + 2 * rp) * jb.N + col;
; #pragma unroll
;     for (int i = 0; i < 8; ++i) { v[i][0] = *(const f32x4*)(wp + (size_t)(32 * i) * jb.N); v[i][1] = *(const f32x4*)(wp + (size_t)(32 * i + 1) * jb.N); }
;     if (jb.gain) {
; #pragma unroll
;         for (int i = 0; i < 8; ++i) { const float ga = jb.gain[k0 + 32 * i + 2 * rp], gb = jb.gain[k0 + 32 * i + 2 * rp + 1]; v[i][0] = v[i][0] * ga; v[i][1] = v[i][1] * gb; } }
; }
.LBB0_1079:
	s_add_i32 s10, s34, 0x7f
	s_lshr_b32 s10, s10, 7
	v_cvt_f32_u32_e32 v2, s10
	s_sub_i32 s15, 0, s10
	s_abs_i32 s14, s30
	s_ashr_i32 s11, s30, 31
	v_rcp_iflag_f32_e32 v2, v2
	s_nop 0
	v_mul_f32_e32 v2, 0x4f7ffffe, v2
	v_cvt_u32_f32_e32 v2, v2
	s_nop 0
	v_readfirstlane_b32 s16, v2
	s_mul_i32 s15, s15, s16
	s_mul_hi_u32 s15, s16, s15
	s_add_i32 s16, s16, s15
	s_mul_hi_u32 s15, s14, s16
	s_mul_i32 s16, s15, s10
	s_sub_i32 s14, s14, s16
	s_add_i32 s17, s15, 1
	s_sub_i32 s16, s14, s10
	s_cmp_ge_u32 s14, s10
	s_cselect_b32 s15, s17, s15
	s_cselect_b32 s14, s16, s14
	s_add_i32 s16, s15, 1
	s_cmp_ge_u32 s14, s10
	s_cselect_b32 s14, s16, s15
	s_xor_b32 s14, s14, s11
	s_sub_i32 s11, s14, s11
	s_mul_i32 s10, s11, s10
	s_lshl_b32 s14, s11, 8
	s_sub_i32 s10, s30, s10
	v_add_u32_e32 v68, s14, v78
	s_lshl_b32 s15, s10, 7
	s_add_i32 s16, s34, -4
	v_or_b32_e32 v2, s15, v77
	v_mad_u64_u32 v[6:7], s[10:11], v68, s34, 0
	v_ashrrev_i32_e32 v69, 31, v68
	v_min_i32_e32 v4, s16, v2
	v_mov_b32_e32 v2, v7
	v_mad_u64_u32 v[8:9], s[10:11], v69, s34, v[2:3]
	v_mov_b32_e32 v7, v8
	v_lshl_add_u64 v[6:7], v[6:7], 2, s[12:13]
	v_ashrrev_i32_e32 v5, 31, v4
	v_lshl_add_u64 v[4:5], v[4:5], 2, v[6:7]
	s_lshl_b64 s[10:11], s[34:35], 2
	v_lshl_add_u64 v[12:13], v[4:5], 0, s[10:11]
	s_mul_i32 s12, s34, 0x7c
	s_mov_b32 s13, s35
	global_load_dwordx4 v[4:7], v[4:5], off sc1 nt
	s_nop 0
	global_load_dwordx4 v[8:11], v[12:13], off sc1 nt
	v_lshl_add_u64 v[12:13], v[12:13], 0, s[12:13]
	v_lshl_add_u64 v[20:21], v[12:13], 0, s[10:11]
	global_load_dwordx4 v[12:15], v[12:13], off sc1 nt
	s_nop 0
	global_load_dwordx4 v[16:19], v[20:21], off sc1 nt
	v_lshl_add_u64 v[20:21], v[20:21], 0, s[12:13]
	v_lshl_add_u64 v[28:29], v[20:21], 0, s[10:11]
	global_load_dwordx4 v[20:23], v[20:21], off sc1 nt
	s_nop 0
	global_load_dwordx4 v[24:27], v[28:29], off sc1 nt
	v_lshl_add_u64 v[28:29], v[28:29], 0, s[12:13]
	v_lshl_add_u64 v[36:37], v[28:29], 0, s[10:11]
	v_lshl_add_u64 v[40:41], v[36:37], 0, s[12:13]
	v_lshl_add_u64 v[44:45], v[40:41], 0, s[10:11]
	v_lshl_add_u64 v[48:49], v[44:45], 0, s[12:13]
	v_lshl_add_u64 v[52:53], v[48:49], 0, s[10:11]
	v_lshl_add_u64 v[56:57], v[52:53], 0, s[12:13]
	v_lshl_add_u64 v[60:61], v[56:57], 0, s[10:11]
	v_lshl_add_u64 v[64:65], v[60:61], 0, s[12:13]
	global_load_dwordx4 v[28:31], v[28:29], off sc1 nt
	s_nop 0
	global_load_dwordx4 v[32:35], v[36:37], off sc1 nt
	s_cmp_eq_u64 s[8:9], 0
	global_load_dwordx4 v[36:39], v[40:41], off sc1 nt
	s_nop 0
	global_load_dwordx4 v[40:43], v[44:45], off sc1 nt
	s_nop 0
	global_load_dwordx4 v[44:47], v[48:49], off sc1 nt
	s_nop 0
	global_load_dwordx4 v[48:51], v[52:53], off sc1 nt
	s_nop 0
	global_load_dwordx4 v[52:55], v[56:57], off sc1 nt
	s_nop 0
	global_load_dwordx4 v[56:59], v[60:61], off sc1 nt
	s_nop 0
	global_load_dwordx4 v[60:63], v[64:65], off sc1 nt
	v_lshl_add_u64 v[64:65], v[64:65], 0, s[10:11]
	global_load_dwordx4 v[64:67], v[64:65], off sc1 nt
	s_cbranch_scc1 .LBB0_1081
	v_lshl_add_u64 v[70:71], v[68:69], 2, s[8:9]
	global_load_dwordx2 v[70:71], v[70:71], off
	s_waitcnt vmcnt(0)
	v_pk_mul_f32 v[6:7], v[6:7], v[70:71] op_sel_hi:[1,0]
	v_pk_mul_f32 v[4:5], v[4:5], v[70:71] op_sel_hi:[1,0]
	v_pk_mul_f32 v[10:11], v[10:11], v[70:71] op_sel:[0,1]
	v_pk_mul_f32 v[8:9], v[8:9], v[70:71] op_sel:[0,1]
	v_add_u32_e32 v70, 32, v68
	v_ashrrev_i32_e32 v71, 31, v70
	v_lshl_add_u64 v[70:71], v[70:71], 2, s[8:9]
	global_load_dwordx2 v[70:71], v[70:71], off
	s_waitcnt vmcnt(0)
	v_pk_mul_f32 v[14:15], v[14:15], v[70:71] op_sel_hi:[1,0]
	v_pk_mul_f32 v[12:13], v[12:13], v[70:71] op_sel_hi:[1,0]
	v_pk_mul_f32 v[18:19], v[18:19], v[70:71] op_sel:[0,1]
	v_pk_mul_f32 v[16:17], v[16:17], v[70:71] op_sel:[0,1]
	v_add_u32_e32 v70, 64, v68
	v_ashrrev_i32_e32 v71, 31, v70
	v_lshl_add_u64 v[70:71], v[70:71], 2, s[8:9]
	global_load_dwordx2 v[70:71], v[70:71], off
	s_waitcnt vmcnt(0)
	v_pk_mul_f32 v[22:23], v[22:23], v[70:71] op_sel_hi:[1,0]
	v_pk_mul_f32 v[20:21], v[20:21], v[70:71] op_sel_hi:[1,0]
	v_pk_mul_f32 v[26:27], v[26:27], v[70:71] op_sel:[0,1]
	v_pk_mul_f32 v[24:25], v[24:25], v[70:71] op_sel:[0,1]
	v_add_u32_e32 v70, 0x60, v68
	v_ashrrev_i32_e32 v71, 31, v70
	v_lshl_add_u64 v[70:71], v[70:71], 2, s[8:9]
	global_load_dwordx2 v[70:71], v[70:71], off
	s_waitcnt vmcnt(0)
	v_pk_mul_f32 v[30:31], v[30:31], v[70:71] op_sel_hi:[1,0]
	v_pk_mul_f32 v[28:29], v[28:29], v[70:71] op_sel_hi:[1,0]
	v_pk_mul_f32 v[34:35], v[34:35], v[70:71] op_sel:[0,1]
	v_pk_mul_f32 v[32:33], v[32:33], v[70:71] op_sel:[0,1]
	v_add_u32_e32 v70, 0x80, v68
	v_ashrrev_i32_e32 v71, 31, v70
	v_lshl_add_u64 v[70:71], v[70:71], 2, s[8:9]
	global_load_dwordx2 v[70:71], v[70:71], off
	s_waitcnt vmcnt(0)
	v_pk_mul_f32 v[38:39], v[38:39], v[70:71] op_sel_hi:[1,0]
	v_pk_mul_f32 v[36:37], v[36:37], v[70:71] op_sel_hi:[1,0]
	v_pk_mul_f32 v[42:43], v[42:43], v[70:71] op_sel:[0,1]
	v_pk_mul_f32 v[40:41], v[40:41], v[70:71] op_sel:[0,1]
	v_add_u32_e32 v70, 0xa0, v68
	v_ashrrev_i32_e32 v71, 31, v70
	v_lshl_add_u64 v[70:71], v[70:71], 2, s[8:9]
	global_load_dwordx2 v[70:71], v[70:71], off
	s_waitcnt vmcnt(0)
	v_pk_mul_f32 v[46:47], v[46:47], v[70:71] op_sel_hi:[1,0]
	v_pk_mul_f32 v[44:45], v[44:45], v[70:71] op_sel_hi:[1,0]
	v_pk_mul_f32 v[50:51], v[50:51], v[70:71] op_sel:[0,1]
	v_pk_mul_f32 v[48:49], v[48:49], v[70:71] op_sel:[0,1]
	v_add_u32_e32 v70, 0xc0, v68
	v_add_u32_e32 v68, 0xe0, v68
	v_ashrrev_i32_e32 v71, 31, v70
	v_ashrrev_i32_e32 v69, 31, v68
	v_lshl_add_u64 v[70:71], v[70:71], 2, s[8:9]
	v_lshl_add_u64 v[68:69], v[68:69], 2, s[8:9]
	global_load_dwordx2 v[70:71], v[70:71], off
	s_nop 0
	global_load_dwordx2 v[68:69], v[68:69], off
	s_waitcnt vmcnt(1)
	v_pk_mul_f32 v[54:55], v[54:55], v[70:71] op_sel_hi:[1,0]
	v_pk_mul_f32 v[52:53], v[52:53], v[70:71] op_sel_hi:[1,0]
	v_pk_mul_f32 v[58:59], v[58:59], v[70:71] op_sel:[0,1]
	v_pk_mul_f32 v[56:57], v[56:57], v[70:71] op_sel:[0,1]
	s_waitcnt vmcnt(0)
	v_pk_mul_f32 v[62:63], v[62:63], v[68:69] op_sel_hi:[1,0]
	v_pk_mul_f32 v[60:61], v[60:61], v[68:69] op_sel_hi:[1,0]
	v_pk_mul_f32 v[66:67], v[66:67], v[68:69] op_sel:[0,1]
	v_pk_mul_f32 v[64:65], v[64:65], v[68:69] op_sel:[0,1]

; __device__ __forceinline__ void tr_load(const TrJob& jb, int tile, int tid, f32x4 (&v)[8][2], int& k0, int& n0) {
;     const int nblk = (jb.N + 127) / 128, kt = tile / nblk, nt = tile - kt * nblk; k0 = 256 * kt; n0 = 128 * nt;
;     const int c4 = (tid & 15) + 16 * ((tid >> 6) & 1), rp = ((tid >> 4) & 3) + 4 * (tid >> 7);
;     int col = n0 + 4 * c4; col = col < jb.N - 4 ? col : jb.N - 4;
;     const float* wp = jb.W + (size_t)(k0 + 2 * rp) * jb.N + col;
; #pragma unroll
;     for (int i = 0; i < 8; ++i) { v[i][0] = *(const f32x4*)(wp + (size_t)(32 * i) * jb.N); v[i][1] = *(const f32x4*)(wp + (size_t)(32 * i + 1) * jb.N); }
;     if (jb.gain) {
; #pragma unroll
;         for (int i = 0; i < 8; ++i) { const float ga = jb.gain[k0 + 32 * i + 2 * rp], gb = jb.gain[k0 + 32 * i + 2 * rp + 1]; v[i][0] = v[i][0] * ga; v[i][1] = v[i][1] * gb; } }
; }
.LBB0_1614:
	s_add_i32 s6, s34, 0x7f
	s_lshr_b32 s6, s6, 7
	v_cvt_f32_u32_e32 v4, s6
	s_sub_i32 s9, 0, s6
	s_abs_i32 s8, s15
	s_ashr_i32 s7, s15, 31
	v_rcp_iflag_f32_e32 v4, v4
	v_lshrrev_b32_e32 v5, 4, v2
	v_ashrrev_i32_e32 v72, 5, v2
	v_bfi_b32 v5, 3, v5, v72
	v_mul_f32_e32 v4, 0x4f7ffffe, v4
	v_cvt_u32_f32_e32 v4, v4
	v_and_b32_e32 v71, 64, v2
	v_lshlrev_b32_e32 v78, 1, v5
	v_readfirstlane_b32 s12, v4
	s_mul_i32 s9, s9, s12
	s_mul_hi_u32 s9, s12, s9
	s_add_i32 s12, s12, s9
	s_mul_hi_u32 s9, s8, s12
	s_mul_i32 s12, s9, s6
	s_sub_i32 s8, s8, s12
	s_add_i32 s13, s9, 1
	s_sub_i32 s12, s8, s6
	s_cmp_ge_u32 s8, s6
	s_cselect_b32 s9, s13, s9
	s_cselect_b32 s8, s12, s8
	s_add_i32 s12, s9, 1
	s_cmp_ge_u32 s8, s6
	s_cselect_b32 s8, s12, s9
	s_xor_b32 s8, s8, s7
	s_sub_i32 s7, s8, s7
	s_mul_i32 s6, s7, s6
	s_sub_i32 s6, s15, s6
	v_lshlrev_b32_e32 v4, 2, v2
	s_lshl_b32 s14, s7, 8
	s_lshl_b32 s15, s6, 7
	v_and_or_b32 v77, v4, 60, v71
	v_or_b32_e32 v4, s15, v77
	s_add_i32 s6, s34, -4
	v_add_u32_e32 v68, s14, v78
	v_min_i32_e32 v4, s6, v4
	s_waitcnt vmcnt(12)
	v_mad_u64_u32 v[6:7], s[6:7], v68, s34, 0
	v_ashrrev_i32_e32 v69, 31, v68
	v_mov_b32_e32 v8, v7
	v_mad_u64_u32 v[8:9], s[6:7], v69, s34, v[8:9]
	v_mov_b32_e32 v7, v8
	v_lshl_add_u64 v[6:7], v[6:7], 2, s[4:5]
	v_ashrrev_i32_e32 v5, 31, v4
	v_lshl_add_u64 v[4:5], v[4:5], 2, v[6:7]
	s_lshl_b64 s[4:5], s[34:35], 2
	s_waitcnt vmcnt(11)
	v_lshl_add_u64 v[12:13], v[4:5], 0, s[4:5]
	s_mul_i32 s6, s34, 0x7c
	s_mov_b32 s7, s35
	global_load_dwordx4 v[4:7], v[4:5], off sc1 nt
	s_nop 0
	global_load_dwordx4 v[8:11], v[12:13], off sc1 nt
	v_lshl_add_u64 v[12:13], v[12:13], 0, s[6:7]
	s_waitcnt vmcnt(11)
	v_lshl_add_u64 v[20:21], v[12:13], 0, s[4:5]
	global_load_dwordx4 v[12:15], v[12:13], off sc1 nt
	s_nop 0
	global_load_dwordx4 v[16:19], v[20:21], off sc1 nt
	v_lshl_add_u64 v[20:21], v[20:21], 0, s[6:7]
	s_waitcnt vmcnt(12)
	v_lshl_add_u64 v[28:29], v[20:21], 0, s[4:5]
	global_load_dwordx4 v[20:23], v[20:21], off sc1 nt
	s_nop 0
	global_load_dwordx4 v[24:27], v[28:29], off sc1 nt
	v_lshl_add_u64 v[28:29], v[28:29], 0, s[6:7]
	s_waitcnt vmcnt(13)
	v_lshl_add_u64 v[36:37], v[28:29], 0, s[4:5]
	s_waitcnt vmcnt(12)
	v_lshl_add_u64 v[40:41], v[36:37], 0, s[6:7]
	s_waitcnt vmcnt(11)
	v_lshl_add_u64 v[44:45], v[40:41], 0, s[4:5]
	s_waitcnt vmcnt(10)
	v_lshl_add_u64 v[48:49], v[44:45], 0, s[6:7]
	s_waitcnt vmcnt(9)
	v_lshl_add_u64 v[52:53], v[48:49], 0, s[4:5]
	s_waitcnt vmcnt(8)
	v_lshl_add_u64 v[56:57], v[52:53], 0, s[6:7]
	s_waitcnt vmcnt(7)
	v_lshl_add_u64 v[60:61], v[56:57], 0, s[4:5]
	s_waitcnt vmcnt(6)
	v_lshl_add_u64 v[64:65], v[60:61], 0, s[6:7]
	global_load_dwordx4 v[28:31], v[28:29], off sc1 nt
	s_nop 0
	global_load_dwordx4 v[32:35], v[36:37], off sc1 nt
	s_cmp_eq_u64 s[10:11], 0
	global_load_dwordx4 v[36:39], v[40:41], off sc1 nt
	s_nop 0
	global_load_dwordx4 v[40:43], v[44:45], off sc1 nt
	s_nop 0
	global_load_dwordx4 v[44:47], v[48:49], off sc1 nt
	s_nop 0
	global_load_dwordx4 v[48:51], v[52:53], off sc1 nt
	s_nop 0
	global_load_dwordx4 v[52:55], v[56:57], off sc1 nt
	s_nop 0
	global_load_dwordx4 v[56:59], v[60:61], off sc1 nt
	s_nop 0
	global_load_dwordx4 v[60:63], v[64:65], off sc1 nt
	v_lshl_add_u64 v[64:65], v[64:65], 0, s[4:5]
	global_load_dwordx4 v[64:67], v[64:65], off sc1 nt
	s_cbranch_scc1 .LBB0_1616
	v_lshl_add_u64 v[68:69], v[68:69], 2, s[10:11]
	global_load_dwordx2 v[74:75], v[68:69], off
	s_waitcnt vmcnt(0)
	v_pk_mul_f32 v[6:7], v[6:7], v[74:75] op_sel_hi:[1,0]
	v_pk_mul_f32 v[4:5], v[4:5], v[74:75] op_sel_hi:[1,0]
	v_pk_mul_f32 v[10:11], v[10:11], v[74:75] op_sel:[0,1]
	v_pk_mul_f32 v[8:9], v[8:9], v[74:75] op_sel:[0,1]
	global_load_dwordx2 v[74:75], v[68:69], off offset:128
	s_waitcnt vmcnt(0)
	v_pk_mul_f32 v[14:15], v[14:15], v[74:75] op_sel_hi:[1,0]
	v_pk_mul_f32 v[12:13], v[12:13], v[74:75] op_sel_hi:[1,0]
	v_pk_mul_f32 v[18:19], v[18:19], v[74:75] op_sel:[0,1]
	v_pk_mul_f32 v[16:17], v[16:17], v[74:75] op_sel:[0,1]
	global_load_dwordx2 v[74:75], v[68:69], off offset:256
	s_waitcnt vmcnt(0)
	v_pk_mul_f32 v[22:23], v[22:23], v[74:75] op_sel_hi:[1,0]
	v_pk_mul_f32 v[20:21], v[20:21], v[74:75] op_sel_hi:[1,0]
	v_pk_mul_f32 v[26:27], v[26:27], v[74:75] op_sel:[0,1]
	v_pk_mul_f32 v[24:25], v[24:25], v[74:75] op_sel:[0,1]
	global_load_dwordx2 v[74:75], v[68:69], off offset:384
	s_waitcnt vmcnt(0)
	v_pk_mul_f32 v[30:31], v[30:31], v[74:75] op_sel_hi:[1,0]
	v_pk_mul_f32 v[28:29], v[28:29], v[74:75] op_sel_hi:[1,0]
	v_pk_mul_f32 v[34:35], v[34:35], v[74:75] op_sel:[0,1]
	v_pk_mul_f32 v[32:33], v[32:33], v[74:75] op_sel:[0,1]
	global_load_dwordx2 v[74:75], v[68:69], off offset:512
	s_waitcnt vmcnt(0)
	v_pk_mul_f32 v[38:39], v[38:39], v[74:75] op_sel_hi:[1,0]
	v_pk_mul_f32 v[36:37], v[36:37], v[74:75] op_sel_hi:[1,0]
	v_pk_mul_f32 v[42:43], v[42:43], v[74:75] op_sel:[0,1]
	v_pk_mul_f32 v[40:41], v[40:41], v[74:75] op_sel:[0,1]
	global_load_dwordx2 v[74:75], v[68:69], off offset:640
	s_waitcnt vmcnt(0)
	v_pk_mul_f32 v[46:47], v[46:47], v[74:75] op_sel_hi:[1,0]
	v_pk_mul_f32 v[44:45], v[44:45], v[74:75] op_sel_hi:[1,0]
	v_pk_mul_f32 v[50:51], v[50:51], v[74:75] op_sel:[0,1]
	v_pk_mul_f32 v[48:49], v[48:49], v[74:75] op_sel:[0,1]
	global_load_dwordx2 v[74:75], v[68:69], off offset:768
	s_waitcnt vmcnt(0)
	v_pk_mul_f32 v[54:55], v[54:55], v[74:75] op_sel_hi:[1,0]
	global_load_dwordx2 v[68:69], v[68:69], off offset:896
	v_pk_mul_f32 v[52:53], v[52:53], v[74:75] op_sel_hi:[1,0]
	v_pk_mul_f32 v[58:59], v[58:59], v[74:75] op_sel:[0,1]
	v_pk_mul_f32 v[56:57], v[56:57], v[74:75] op_sel:[0,1]
	s_waitcnt vmcnt(0)
	v_pk_mul_f32 v[62:63], v[62:63], v[68:69] op_sel_hi:[1,0]
	v_pk_mul_f32 v[60:61], v[60:61], v[68:69] op_sel_hi:[1,0]
	v_pk_mul_f32 v[66:67], v[66:67], v[68:69] op_sel:[0,1]
	v_pk_mul_f32 v[64:65], v[64:65], v[68:69] op_sel:[0,1]
